# grid barrier: all workgroups wait on the top-level arrival counter reaching (gen+1)*nx; generation-word increment removed from the critical path
# baseline (speedup 1.0000x reference)
.LBB0_209:
	s_or_b64 exec, exec, s[8:9]
	v_cvt_f32_u32_e32 v4, v2
	s_waitcnt vmcnt(0)
	v_readfirstlane_b32 s6, v3
	v_sub_u32_e32 v3, 0, v2
	v_rcp_iflag_f32_e32 v4, v4
	v_add_u32_e32 v5, s6, v1
	v_mul_f32_e32 v4, 0x4f7ffffe, v4
	v_cvt_u32_f32_e32 v4, v4
	v_mul_lo_u32 v1, v3, v4
	v_mul_hi_u32 v1, v4, v1
	v_add_u32_e32 v1, v4, v1
	v_mul_hi_u32 v1, v5, v1
	v_mul_lo_u32 v3, v1, v2
	v_sub_u32_e32 v3, v5, v3
	v_add_u32_e32 v4, 1, v1
	v_cmp_ge_u32_e32 vcc, v3, v2
	s_nop 1
	v_cndmask_b32_e32 v1, v1, v4, vcc
	v_sub_u32_e32 v4, v3, v2
	v_cndmask_b32_e32 v3, v3, v4, vcc
	v_add_u32_e32 v4, 1, v1
	v_cmp_ge_u32_e32 vcc, v3, v2
	v_add_u32_e32 v3, 1, v5
	s_nop 0
	v_cndmask_b32_e32 v1, v1, v4, vcc
	v_mul_lo_u32 v4, v2, v1
	v_add_u32_e32 v2, v4, v2
	v_cmp_ne_u32_e32 vcc, v3, v2
	s_and_saveexec_b64 s[6:7], vcc
	s_xor_b64 s[6:7], exec, s[6:7]
	s_cbranch_execz .LBB0_223
	s_waitcnt lgkmcnt(0)
	v_add_u32_e32 v3, 1, v1
	v_mul_lo_u32 v1, v3, v0
	v_mov_b32_e32 v0, 0
	s_add_u32 s12, s22, 0x194d0400
	s_addc_u32 s13, s23, 0
	global_load_dword v0, v0, s[12:13] sc1
	s_waitcnt vmcnt(0)
	v_cmp_lt_u32_e32 vcc, v0, v1
	s_and_saveexec_b64 s[8:9], vcc
	s_cbranch_execz .LBB0_222
	s_add_u32 s10, s22, 0x194cd200
	s_addc_u32 s11, s23, 0
	s_mov_b32 s28, 1
	s_mov_b64 s[14:15], 0
	v_mov_b32_e32 v0, 0
	s_branch .LBB0_213

.LBB0_217:
	global_load_dword v2, v0, s[12:13] sc1
	s_add_i32 s28, s28, 1
	s_mov_b64 s[24:25], -1
	s_waitcnt vmcnt(0)
	v_cmp_ge_u32_e32 vcc, v2, v1
	s_orn2_b64 s[18:19], vcc, exec
	s_branch .LBB0_212

.LBB0_226:
	s_or_b64 exec, exec, s[8:9]
	v_cvt_f32_u32_e32 v3, v0
	s_waitcnt vmcnt(0)
	v_readfirstlane_b32 s6, v2
	s_add_u32 s8, s22, 0x194d0500
	s_addc_u32 s9, s23, 0
	v_rcp_iflag_f32_e32 v3, v3
	v_add_u32_e32 v1, s6, v1
	v_add_u32_e32 v4, 1, v1
	s_mov_b64 s[10:11], 0
	v_mul_f32_e32 v2, 0x4f7ffffe, v3
	v_cvt_u32_f32_e32 v2, v2
	v_sub_u32_e32 v3, 0, v0
	v_mul_lo_u32 v3, v3, v2
	v_mul_hi_u32 v3, v2, v3
	v_add_u32_e32 v2, v2, v3
	v_mul_hi_u32 v2, v1, v2
	v_mul_lo_u32 v3, v2, v0
	v_sub_u32_e32 v1, v1, v3
	v_add_u32_e32 v5, 1, v2
	v_cmp_ge_u32_e32 vcc, v1, v0
	v_sub_u32_e32 v3, v1, v0
	s_nop 0
	v_cndmask_b32_e32 v2, v2, v5, vcc
	v_cndmask_b32_e32 v1, v1, v3, vcc
	v_add_u32_e32 v3, 1, v2
	v_cmp_ge_u32_e32 vcc, v1, v0
	s_nop 1
	v_cndmask_b32_e32 v2, v2, v3, vcc
	v_mul_lo_u32 v1, v0, v2
	v_add_u32_e32 v0, v1, v0
	v_cmp_ne_u32_e32 vcc, v4, v0
	v_mov_b32_e32 v5, v0
	v_mov_b64_e32 v[0:1], s[8:9]
	s_and_saveexec_b64 s[6:7], vcc
	s_cbranch_execz .LBB0_238
	v_mov_b32_e32 v0, 0
	global_load_dword v1, v0, s[8:9] offset:-256 sc1
	s_mov_b64 s[14:15], 0
	s_waitcnt vmcnt(0)
	v_cmp_lt_u32_e32 vcc, v1, v5
	s_and_saveexec_b64 s[12:13], vcc
	s_cbranch_execz .LBB0_237
	s_add_u32 s10, s22, 0x194cd200
	s_addc_u32 s11, s23, 0
	s_mov_b32 s28, 1
	s_branch .LBB0_230

.LBB0_234:
	global_load_dword v1, v0, s[8:9] offset:-256 sc1
	s_add_i32 s28, s28, 1
	s_mov_b64 s[18:19], -1
	s_waitcnt vmcnt(0)
	v_cmp_ge_u32_e32 vcc, v1, v5
	s_orn2_b64 s[26:27], vcc, exec
	s_branch .LBB0_229

.LBB0_682:
	s_or_b64 exec, exec, s[10:11]
	v_cvt_f32_u32_e32 v4, v2
	s_waitcnt vmcnt(0)
	v_readfirstlane_b32 s8, v3
	v_sub_u32_e32 v3, 0, v2
	v_rcp_iflag_f32_e32 v4, v4
	v_add_u32_e32 v5, s8, v1
	v_mul_f32_e32 v4, 0x4f7ffffe, v4
	v_cvt_u32_f32_e32 v4, v4
	v_mul_lo_u32 v1, v3, v4
	v_mul_hi_u32 v1, v4, v1
	v_add_u32_e32 v1, v4, v1
	v_mul_hi_u32 v1, v5, v1
	v_mul_lo_u32 v3, v1, v2
	v_sub_u32_e32 v3, v5, v3
	v_add_u32_e32 v4, 1, v1
	v_cmp_ge_u32_e32 vcc, v3, v2
	s_nop 1
	v_cndmask_b32_e32 v1, v1, v4, vcc
	v_sub_u32_e32 v4, v3, v2
	v_cndmask_b32_e32 v3, v3, v4, vcc
	v_add_u32_e32 v4, 1, v1
	v_cmp_ge_u32_e32 vcc, v3, v2
	v_add_u32_e32 v3, 1, v5
	s_nop 0
	v_cndmask_b32_e32 v1, v1, v4, vcc
	v_mul_lo_u32 v4, v2, v1
	v_add_u32_e32 v2, v4, v2
	v_cmp_ne_u32_e32 vcc, v3, v2
	s_and_saveexec_b64 s[8:9], vcc
	s_xor_b64 s[8:9], exec, s[8:9]
	s_cbranch_execz .LBB0_696
	s_waitcnt lgkmcnt(0)
	v_add_u32_e32 v3, 1, v1
	v_mul_lo_u32 v1, v3, v0
	v_mov_b32_e32 v0, 0
	s_add_u32 s14, s22, 0x194d0400
	s_addc_u32 s15, s23, 0
	global_load_dword v0, v0, s[14:15] sc1
	s_waitcnt vmcnt(0)
	v_cmp_lt_u32_e32 vcc, v0, v1
	s_and_saveexec_b64 s[10:11], vcc
	s_cbranch_execz .LBB0_695
	s_add_u32 s12, s22, 0x194cd200
	s_addc_u32 s13, s23, 0
	s_mov_b32 s30, 1
	s_mov_b64 s[16:17], 0
	v_mov_b32_e32 v0, 0
	s_branch .LBB0_686

.LBB0_690:
	global_load_dword v2, v0, s[14:15] sc1
	s_add_i32 s30, s30, 1
	s_mov_b64 s[26:27], -1
	s_waitcnt vmcnt(0)
	v_cmp_ge_u32_e32 vcc, v2, v1
	s_orn2_b64 s[24:25], vcc, exec
	s_branch .LBB0_685

.LBB0_699:
	s_or_b64 exec, exec, s[10:11]
	v_cvt_f32_u32_e32 v3, v0
	s_waitcnt vmcnt(0)
	v_readfirstlane_b32 s8, v2
	s_add_u32 s10, s22, 0x194d0500
	s_addc_u32 s11, s23, 0
	v_rcp_iflag_f32_e32 v3, v3
	v_add_u32_e32 v1, s8, v1
	v_add_u32_e32 v4, 1, v1
	s_mov_b64 s[12:13], 0
	v_mul_f32_e32 v2, 0x4f7ffffe, v3
	v_cvt_u32_f32_e32 v2, v2
	v_sub_u32_e32 v3, 0, v0
	v_mul_lo_u32 v3, v3, v2
	v_mul_hi_u32 v3, v2, v3
	v_add_u32_e32 v2, v2, v3
	v_mul_hi_u32 v2, v1, v2
	v_mul_lo_u32 v3, v2, v0
	v_sub_u32_e32 v1, v1, v3
	v_add_u32_e32 v5, 1, v2
	v_cmp_ge_u32_e32 vcc, v1, v0
	v_sub_u32_e32 v3, v1, v0
	s_nop 0
	v_cndmask_b32_e32 v2, v2, v5, vcc
	v_cndmask_b32_e32 v1, v1, v3, vcc
	v_add_u32_e32 v3, 1, v2
	v_cmp_ge_u32_e32 vcc, v1, v0
	s_nop 1
	v_cndmask_b32_e32 v2, v2, v3, vcc
	v_mul_lo_u32 v1, v0, v2
	v_add_u32_e32 v0, v1, v0
	v_cmp_ne_u32_e32 vcc, v4, v0
	v_mov_b32_e32 v5, v0
	v_mov_b64_e32 v[0:1], s[10:11]
	s_and_saveexec_b64 s[8:9], vcc
	s_cbranch_execz .LBB0_711
	v_mov_b32_e32 v0, 0
	global_load_dword v1, v0, s[10:11] offset:-256 sc1
	s_mov_b64 s[16:17], 0
	s_waitcnt vmcnt(0)
	v_cmp_lt_u32_e32 vcc, v1, v5
	s_and_saveexec_b64 s[14:15], vcc
	s_cbranch_execz .LBB0_710
	s_add_u32 s12, s22, 0x194cd200
	s_addc_u32 s13, s23, 0
	s_mov_b32 s30, 1
	s_branch .LBB0_703

.LBB0_707:
	global_load_dword v1, v0, s[10:11] offset:-256 sc1
	s_add_i32 s30, s30, 1
	s_mov_b64 s[24:25], -1
	s_waitcnt vmcnt(0)
	v_cmp_ge_u32_e32 vcc, v1, v5
	s_orn2_b64 s[28:29], vcc, exec
	s_branch .LBB0_702

.LBB0_1291:
	s_or_b64 exec, exec, s[10:11]
	v_cvt_f32_u32_e32 v4, v2
	s_waitcnt vmcnt(0)
	v_readfirstlane_b32 s8, v3
	v_sub_u32_e32 v3, 0, v2
	v_rcp_iflag_f32_e32 v4, v4
	v_add_u32_e32 v5, s8, v1
	v_mul_f32_e32 v4, 0x4f7ffffe, v4
	v_cvt_u32_f32_e32 v4, v4
	v_mul_lo_u32 v1, v3, v4
	v_mul_hi_u32 v1, v4, v1
	v_add_u32_e32 v1, v4, v1
	v_mul_hi_u32 v1, v5, v1
	v_mul_lo_u32 v3, v1, v2
	v_sub_u32_e32 v3, v5, v3
	v_add_u32_e32 v4, 1, v1
	v_cmp_ge_u32_e32 vcc, v3, v2
	s_nop 1
	v_cndmask_b32_e32 v1, v1, v4, vcc
	v_sub_u32_e32 v4, v3, v2
	v_cndmask_b32_e32 v3, v3, v4, vcc
	v_add_u32_e32 v4, 1, v1
	v_cmp_ge_u32_e32 vcc, v3, v2
	v_add_u32_e32 v3, 1, v5
	s_nop 0
	v_cndmask_b32_e32 v1, v1, v4, vcc
	v_mul_lo_u32 v4, v2, v1
	v_add_u32_e32 v2, v4, v2
	v_cmp_ne_u32_e32 vcc, v3, v2
	s_and_saveexec_b64 s[8:9], vcc
	s_xor_b64 s[8:9], exec, s[8:9]
	s_cbranch_execz .LBB0_1305
	s_waitcnt lgkmcnt(0)
	v_add_u32_e32 v3, 1, v1
	v_mul_lo_u32 v1, v3, v0
	v_mov_b32_e32 v0, 0
	s_add_u32 s14, s22, 0x194d0400
	s_addc_u32 s15, s23, 0
	global_load_dword v0, v0, s[14:15] sc1
	s_waitcnt vmcnt(0)
	v_cmp_lt_u32_e32 vcc, v0, v1
	s_and_saveexec_b64 s[10:11], vcc
	s_cbranch_execz .LBB0_1304
	s_add_u32 s12, s22, 0x194cd200
	s_mov_b32 s34, s30
	s_addc_u32 s13, s23, 0
	s_mov_b32 s30, 1
	s_mov_b64 s[16:17], 0
	v_mov_b32_e32 v0, 0
	s_branch .LBB0_1295

.LBB0_1308:
	s_or_b64 exec, exec, s[10:11]
	v_cvt_f32_u32_e32 v3, v0
	s_waitcnt vmcnt(0)
	v_readfirstlane_b32 s8, v2
	s_add_u32 s10, s22, 0x194d0500
	s_addc_u32 s11, s23, 0
	v_rcp_iflag_f32_e32 v3, v3
	v_add_u32_e32 v1, s8, v1
	v_add_u32_e32 v4, 1, v1
	s_mov_b64 s[12:13], 0
	v_mul_f32_e32 v2, 0x4f7ffffe, v3
	v_cvt_u32_f32_e32 v2, v2
	v_sub_u32_e32 v3, 0, v0
	v_mul_lo_u32 v3, v3, v2
	v_mul_hi_u32 v3, v2, v3
	v_add_u32_e32 v2, v2, v3
	v_mul_hi_u32 v2, v1, v2
	v_mul_lo_u32 v3, v2, v0
	v_sub_u32_e32 v1, v1, v3
	v_add_u32_e32 v5, 1, v2
	v_cmp_ge_u32_e32 vcc, v1, v0
	v_sub_u32_e32 v3, v1, v0
	s_nop 0
	v_cndmask_b32_e32 v2, v2, v5, vcc
	v_cndmask_b32_e32 v1, v1, v3, vcc
	v_add_u32_e32 v3, 1, v2
	v_cmp_ge_u32_e32 vcc, v1, v0
	s_nop 1
	v_cndmask_b32_e32 v2, v2, v3, vcc
	v_mul_lo_u32 v1, v0, v2
	v_add_u32_e32 v0, v1, v0
	v_cmp_ne_u32_e32 vcc, v4, v0
	v_mov_b32_e32 v5, v0
	v_mov_b64_e32 v[0:1], s[10:11]
	s_and_saveexec_b64 s[8:9], vcc
	s_cbranch_execz .LBB0_1320
	v_mov_b32_e32 v0, 0
	global_load_dword v1, v0, s[10:11] offset:-256 sc1
	s_mov_b64 s[16:17], 0
	s_waitcnt vmcnt(0)
	v_cmp_lt_u32_e32 vcc, v1, v5
	s_and_saveexec_b64 s[14:15], vcc
	s_cbranch_execz .LBB0_1319
	s_add_u32 s12, s22, 0x194cd200
	s_mov_b32 s34, s30
	s_addc_u32 s13, s23, 0
	s_mov_b32 s30, 1
	s_branch .LBB0_1312
